# P1 full-line store transform + sample attention QK: 4 K-fragment LDS reads issued together with counted waits
# speedup vs baseline: 1.0101x; 1.0101x over previous
.LBB0_467:
	ds_read_b128 v[192:195], v187 offset:32768
	ds_read_b128 v[196:199], v188 offset:32768
	ds_read_b128 v[200:203], v189 offset:32768
	ds_read_b128 v[204:207], v190 offset:32768
	v_mov_b32_e32 v67, v82
	s_add_i32 s2, s3, 2
	s_waitcnt lgkmcnt(3)
	v_mfma_f32_32x32x16_bf16 v[66:81], v[192:195], v[84:87], v[66:81]
	s_waitcnt lgkmcnt(2)
	v_mfma_f32_32x32x16_bf16 v[66:81], v[196:199], v[88:91], v[66:81]
	s_waitcnt lgkmcnt(1)
	v_mfma_f32_32x32x16_bf16 v[66:81], v[200:203], v[92:95], v[66:81]
	s_waitcnt lgkmcnt(0)
	v_mfma_f32_32x32x16_bf16 v[66:81], v[204:207], v[96:99], v[66:81]
	s_nop 11
	v_exp_f32_e32 v66, v66
	v_exp_f32_e32 v67, v67
	v_exp_f32_e32 v68, v68
	v_exp_f32_e32 v69, v69
	v_add_f32_e32 v82, 0, v66
	v_exp_f32_e32 v70, v70
	v_add_f32_e32 v82, v67, v82
	v_exp_f32_e32 v71, v71
	v_add_f32_e32 v82, v68, v82
	v_exp_f32_e32 v72, v72
	v_add_f32_e32 v82, v69, v82
	v_exp_f32_e32 v73, v73
	v_add_f32_e32 v82, v70, v82
	v_exp_f32_e32 v74, v74
	v_add_f32_e32 v82, v71, v82
	v_exp_f32_e32 v75, v75
	v_add_f32_e32 v82, v72, v82
	v_exp_f32_e32 v76, v76
	v_add_f32_e32 v82, v73, v82
	v_exp_f32_e32 v77, v77
	v_add_f32_e32 v82, v74, v82
	v_exp_f32_e32 v78, v78
	v_add_f32_e32 v82, v75, v82
	v_exp_f32_e32 v79, v79
	v_add_f32_e32 v82, v76, v82
	v_exp_f32_e32 v80, v80
	v_add_f32_e32 v82, v77, v82
	v_exp_f32_e32 v81, v81
	v_add_f32_e32 v82, v78, v82
	v_add_f32_e32 v82, v79, v82
	v_add_f32_e32 v82, v80, v82
	v_add_f32_e32 v82, v81, v82
	v_add_f32_e32 v182, v182, v82
	v_cvt_pk_bf16_f32 v66, v66, v67
	v_cvt_pk_bf16_f32 v67, v68, v69
	v_cvt_pk_bf16_f32 v68, v70, v71
	v_cvt_pk_bf16_f32 v69, v72, v73
	v_cvt_pk_bf16_f32 v70, v74, v75
	v_cvt_pk_bf16_f32 v71, v76, v77
	v_cvt_pk_bf16_f32 v72, v78, v79
	v_cvt_pk_bf16_f32 v73, v80, v81
	s_nop 0
	v_permlane32_swap_b32_e32 v66, v68
	v_permlane32_swap_b32_e32 v67, v69
	v_permlane32_swap_b32_e32 v70, v72
	v_permlane32_swap_b32_e32 v71, v73
	ds_read_b64_tr_b16 v[74:75], v83 offset:0
	ds_read_b64_tr_b16 v[76:77], v83 offset:0x800
	ds_read_b64_tr_b16 v[78:79], v83 offset:0x1000
	ds_read_b64_tr_b16 v[80:81], v83 offset:0x1800
	s_waitcnt lgkmcnt(0)
	s_nop 0
	v_mfma_f32_32x32x16_bf16 v[2:17], v[66:69], v[74:77], v[2:17]
	ds_read_b64_tr_b16 v[74:75], v83 offset:0x200
	ds_read_b64_tr_b16 v[76:77], v83 offset:0xa00
	v_mfma_f32_32x32x16_bf16 v[2:17], v[70:73], v[78:81], v[2:17]
	ds_read_b64_tr_b16 v[78:79], v83 offset:0x1200
	ds_read_b64_tr_b16 v[80:81], v83 offset:0x1a00
	s_waitcnt lgkmcnt(0)
	v_mfma_f32_32x32x16_bf16 v[50:65], v[66:69], v[74:77], v[50:65]
	ds_read_b64_tr_b16 v[74:75], v83 offset:0x400
	ds_read_b64_tr_b16 v[76:77], v83 offset:0xc00
	v_mfma_f32_32x32x16_bf16 v[50:65], v[70:73], v[78:81], v[50:65]
	ds_read_b64_tr_b16 v[78:79], v83 offset:0x1400
	ds_read_b64_tr_b16 v[80:81], v83 offset:0x1c00
	s_waitcnt lgkmcnt(0)
	v_mfma_f32_32x32x16_bf16 v[18:33], v[66:69], v[74:77], v[18:33]
	ds_read_b64_tr_b16 v[74:75], v83 offset:0x600
	ds_read_b64_tr_b16 v[76:77], v83 offset:0xe00
	v_mfma_f32_32x32x16_bf16 v[18:33], v[70:73], v[78:81], v[18:33]
	ds_read_b64_tr_b16 v[78:79], v83 offset:0x1600
	ds_read_b64_tr_b16 v[80:81], v83 offset:0x1e00
	s_waitcnt lgkmcnt(0)
	s_min_u32 s14, s2, 61
	s_add_i32 s14, s1, s14
	v_mfma_f32_32x32x16_bf16 v[34:49], v[66:69], v[74:77], v[34:49]
	s_add_i32 s3, s3, 3
	s_add_i32 s34, s14, 0xffffffbf
	s_cmp_gt_i32 s14, 64
	s_waitcnt vmcnt(8)
	s_waitcnt vmcnt(14)
	v_cvt_pk_bf16_f32 v66, v160, v161
	v_cvt_pk_bf16_f32 v67, v162, v163
	v_cvt_pk_bf16_f32 v68, v152, v153
	v_cvt_pk_bf16_f32 v69, v154, v155
	s_cselect_b32 s54, s34, s14
	ds_write_b128 v183, v[66:69] offset:16384
	s_waitcnt vmcnt(12)
	v_cvt_pk_bf16_f32 v66, v156, v157
	v_cvt_pk_bf16_f32 v67, v158, v159
	v_cvt_pk_bf16_f32 v68, v140, v141
	v_cvt_pk_bf16_f32 v69, v142, v143
	s_cmp_lt_i32 s54, 64
	ds_write_b128 v184, v[66:69] offset:16384
	s_waitcnt vmcnt(10)
	v_cvt_pk_bf16_f32 v66, v148, v149
	v_cvt_pk_bf16_f32 v67, v150, v151
	v_cvt_pk_bf16_f32 v68, v136, v137
	v_cvt_pk_bf16_f32 v69, v138, v139
	s_cselect_b64 vcc, -1, 0
	s_ashr_i32 s55, s54, 31
	ds_write_b128 v185, v[66:69] offset:49152
	s_waitcnt vmcnt(8)
	v_cvt_pk_bf16_f32 v66, v144, v145
	v_cvt_pk_bf16_f32 v67, v146, v147
	v_cvt_pk_bf16_f32 v68, v132, v133
	v_cvt_pk_bf16_f32 v69, v134, v135
	s_lshl_b64 s[54:55], s[54:55], 18
	ds_write_b128 v186, v[66:69] offset:49152
	v_lshl_add_u64 v[68:69], v[166:167], 0, s[54:55]
	v_lshl_add_u64 v[66:67], v[164:165], 0, s[54:55]
	v_cndmask_b32_e32 v69, v171, v69, vcc
	v_cndmask_b32_e32 v68, v170, v68, vcc
	v_mfma_f32_32x32x16_bf16 v[34:49], v[70:73], v[78:81], v[34:49]
	v_cndmask_b32_e32 v67, v169, v67, vcc
	v_cndmask_b32_e32 v66, v168, v66, vcc
	v_lshl_add_u64 v[70:71], v[68:69], 0, v[172:173]
	v_lshl_add_u64 v[68:69], v[68:69], 0, v[174:175]
	s_waitcnt lgkmcnt(0)
	s_barrier
	global_load_dwordx4 v[152:155], v[70:71], off offset:16
	global_load_dwordx4 v[160:163], v[70:71], off
	global_load_dwordx4 v[140:143], v[68:69], off offset:16
	global_load_dwordx4 v[156:159], v[68:69], off
	v_lshl_add_u64 v[68:69], v[66:67], 0, v[172:173]
	v_lshl_add_u64 v[66:67], v[66:67], 0, v[174:175]
	global_load_dwordx4 v[136:139], v[68:69], off offset:16
	global_load_dwordx4 v[148:151], v[68:69], off
	global_load_dwordx4 v[132:135], v[66:67], off offset:16
	global_load_dwordx4 v[144:147], v[66:67], off
	s_cmp_gt_u32 s3, 64
	s_cbranch_scc1 .LBB0_474
	s_add_i32 s3, s10, 3
	s_sub_i32 s10, s10, 62
	s_cmp_gt_i32 s3, 64
	s_cselect_b32 s3, s10, s3
	s_cmp_lt_i32 s3, 62
	s_cbranch_scc0 .LBB0_470
	v_mov_b32_e32 v66, s35
	ds_read_b32 v82, v66
	s_mov_b64 s[54:55], 0
	s_waitcnt lgkmcnt(0)
	v_mov_b64_e32 v[66:67], v[82:83]
	v_mov_b64_e32 v[68:69], v[84:85]
	v_mov_b64_e32 v[70:71], v[86:87]
	v_mov_b64_e32 v[72:73], v[88:89]
	v_mov_b64_e32 v[74:75], v[90:91]
	v_mov_b64_e32 v[76:77], v[92:93]
	v_mov_b64_e32 v[78:79], v[94:95]
	v_mov_b64_e32 v[80:81], v[96:97]
	s_branch .LBB0_471

.LBB0_473:
	ds_read_b128 v[192:195], v187 offset:49152
	ds_read_b128 v[196:199], v188 offset:49152
	ds_read_b128 v[200:203], v189 offset:49152
	ds_read_b128 v[204:207], v190 offset:49152
	v_mov_b32_e32 v67, v82
	s_waitcnt lgkmcnt(3)
	s_nop 0
	v_mfma_f32_32x32x16_bf16 v[66:81], v[192:195], v[84:87], v[66:81]
	s_waitcnt lgkmcnt(2)
	v_mfma_f32_32x32x16_bf16 v[66:81], v[196:199], v[88:91], v[66:81]
	s_waitcnt lgkmcnt(1)
	v_mfma_f32_32x32x16_bf16 v[66:81], v[200:203], v[92:95], v[66:81]
	s_waitcnt lgkmcnt(0)
	v_mfma_f32_32x32x16_bf16 v[66:81], v[204:207], v[96:99], v[66:81]
	s_nop 11
	v_exp_f32_e32 v66, v66
	v_exp_f32_e32 v67, v67
	v_exp_f32_e32 v68, v68
	v_exp_f32_e32 v69, v69
	v_add_f32_e32 v82, 0, v66
	v_exp_f32_e32 v70, v70
	v_add_f32_e32 v82, v67, v82
	v_exp_f32_e32 v71, v71
	v_add_f32_e32 v82, v68, v82
	v_exp_f32_e32 v72, v72
	v_add_f32_e32 v82, v69, v82
	v_exp_f32_e32 v73, v73
	v_add_f32_e32 v82, v70, v82
	v_exp_f32_e32 v74, v74
	v_add_f32_e32 v82, v71, v82
	v_exp_f32_e32 v75, v75
	v_add_f32_e32 v82, v72, v82
	v_exp_f32_e32 v76, v76
	v_add_f32_e32 v82, v73, v82
	v_exp_f32_e32 v77, v77
	v_add_f32_e32 v82, v74, v82
	v_exp_f32_e32 v78, v78
	v_add_f32_e32 v82, v75, v82
	v_exp_f32_e32 v79, v79
	v_add_f32_e32 v82, v76, v82
	v_exp_f32_e32 v80, v80
	v_add_f32_e32 v82, v77, v82
	v_exp_f32_e32 v81, v81
	v_add_f32_e32 v82, v78, v82
	v_add_f32_e32 v82, v79, v82
	v_add_f32_e32 v82, v80, v82
	v_add_f32_e32 v82, v81, v82
	v_add_f32_e32 v182, v182, v82
	v_cvt_pk_bf16_f32 v66, v66, v67
	v_cvt_pk_bf16_f32 v67, v68, v69
	v_cvt_pk_bf16_f32 v68, v70, v71
	v_cvt_pk_bf16_f32 v69, v72, v73
	v_cvt_pk_bf16_f32 v70, v74, v75
	v_cvt_pk_bf16_f32 v71, v76, v77
	v_cvt_pk_bf16_f32 v72, v78, v79
	v_cvt_pk_bf16_f32 v73, v80, v81
	s_nop 0
	v_permlane32_swap_b32_e32 v66, v68
	v_permlane32_swap_b32_e32 v67, v69
	v_permlane32_swap_b32_e32 v70, v72
	v_permlane32_swap_b32_e32 v71, v73
	ds_read_b64_tr_b16 v[74:75], v180 offset:0
	ds_read_b64_tr_b16 v[76:77], v180 offset:0x800
	ds_read_b64_tr_b16 v[78:79], v180 offset:0x1000
	ds_read_b64_tr_b16 v[80:81], v180 offset:0x1800
	s_waitcnt lgkmcnt(0)
	s_nop 0
	v_mfma_f32_32x32x16_bf16 v[2:17], v[66:69], v[74:77], v[2:17]
	ds_read_b64_tr_b16 v[74:75], v180 offset:0x200
	ds_read_b64_tr_b16 v[76:77], v180 offset:0xa00
	v_mfma_f32_32x32x16_bf16 v[2:17], v[70:73], v[78:81], v[2:17]
	ds_read_b64_tr_b16 v[78:79], v180 offset:0x1200
	ds_read_b64_tr_b16 v[80:81], v180 offset:0x1a00
	s_waitcnt lgkmcnt(0)
	v_mfma_f32_32x32x16_bf16 v[50:65], v[66:69], v[74:77], v[50:65]
	ds_read_b64_tr_b16 v[74:75], v180 offset:0x400
	ds_read_b64_tr_b16 v[76:77], v180 offset:0xc00
	v_mfma_f32_32x32x16_bf16 v[50:65], v[70:73], v[78:81], v[50:65]
	ds_read_b64_tr_b16 v[78:79], v180 offset:0x1400
	ds_read_b64_tr_b16 v[80:81], v180 offset:0x1c00
	s_waitcnt lgkmcnt(0)
	v_mfma_f32_32x32x16_bf16 v[18:33], v[66:69], v[74:77], v[18:33]
	ds_read_b64_tr_b16 v[74:75], v180 offset:0x600
	ds_read_b64_tr_b16 v[76:77], v180 offset:0xe00
	v_mfma_f32_32x32x16_bf16 v[18:33], v[70:73], v[78:81], v[18:33]
	ds_read_b64_tr_b16 v[78:79], v180 offset:0x1600
	ds_read_b64_tr_b16 v[80:81], v180 offset:0x1e00
	s_waitcnt lgkmcnt(0)
	v_mfma_f32_32x32x16_bf16 v[34:49], v[66:69], v[74:77], v[34:49]
	v_mfma_f32_32x32x16_bf16 v[34:49], v[70:73], v[78:81], v[34:49]
